# hand-written SSD conv+SiLU stage (software-pipelined) + attention next-tile K/V prefetch
# speedup vs baseline: 1.0428x; 1.0085x over previous
.LBB0_889:
	s_waitcnt vmcnt(0)
	v_cvt_pk_bf16_f32 v31, v30, v31
	v_cvt_pk_bf16_f32 v30, v28, v29
	v_cvt_pk_bf16_f32 v29, v38, v39
	v_cvt_pk_bf16_f32 v28, v36, v37
	ds_write_b128 v76, v[28:31] offset:16
	s_cmp_lg_u64 s[12:13], 0
	s_cbranch_scc0 .Lapf0_c
	v_add_u32_e32 v242, s26, v66
	v_add_u32_e32 v242, 64, v242
	v_mad_i64_i32 v[242:243], s[100:101], v242, s70, v[52:53]
	global_load_dword v244, v[242:243], off offset:1024
	global_load_dword v245, v[242:243], off offset:768
	s_branch .Lapf0_d
.Lapf0_c:
	s_cmp_lt_u32 s26, 0xc0
	s_cbranch_scc0 .Lapf0_d
	v_add_u32_e32 v242, s26, v65
	v_add_u32_e32 v242, 64, v242
	v_ashrrev_i32_e32 v243, 31, v242
	v_lshlrev_b64 v[242:243], 9, v[242:243]
	v_lshl_add_u64 v[244:245], v[48:49], 0, v[242:243]
	v_lshl_add_u64 v[242:243], v[50:51], 0, v[242:243]
	global_load_dword v244, v[244:245], off
	global_load_dword v242, v[242:243], off
.Lapf0_d:
	s_waitcnt lgkmcnt(0)
	s_barrier
	ds_read_b128 v[28:31], v77
	ds_read_b128 v[32:35], v77 offset:64
	s_waitcnt lgkmcnt(1)
	v_mfma_f32_16x16x32_bf16 v[28:31], v[4:7], v[28:31], 0
	s_and_b64 s[6:7], s[0:1], s[12:13]
	s_andn2_b64 vcc, exec, s[6:7]
	s_waitcnt lgkmcnt(0)
	v_mfma_f32_16x16x32_bf16 v[28:31], v[8:11], v[32:35], v[28:31]
	ds_read_b128 v[32:35], v77 offset:2304
	ds_read_b128 v[36:39], v77 offset:2368
	s_waitcnt lgkmcnt(1)
	v_mfma_f32_16x16x32_bf16 v[32:35], v[4:7], v[32:35], 0
	s_waitcnt lgkmcnt(0)
	v_mfma_f32_16x16x32_bf16 v[32:35], v[8:11], v[36:39], v[32:35]
	ds_read_b128 v[36:39], v77 offset:4608
	ds_read_b128 v[40:43], v77 offset:4672
	s_waitcnt lgkmcnt(1)
	v_mfma_f32_16x16x32_bf16 v[36:39], v[4:7], v[36:39], 0
	s_waitcnt lgkmcnt(0)
	v_mfma_f32_16x16x32_bf16 v[36:39], v[8:11], v[40:43], v[36:39]
	ds_read_b128 v[40:43], v77 offset:6912
	ds_read_b128 v[56:59], v77 offset:6976
	s_waitcnt lgkmcnt(1)
	v_mfma_f32_16x16x32_bf16 v[40:43], v[4:7], v[40:43], 0
	s_waitcnt lgkmcnt(0)
	v_mfma_f32_16x16x32_bf16 v[40:43], v[8:11], v[56:59], v[40:43]
	s_cbranch_vccnz .LBB0_870
	v_add_u32_e32 v56, s26, v45
	v_sub_u32_e32 v57, v69, v56
	v_sub_u32_e32 v58, 0, v57
	v_max_i32_e32 v58, v57, v58
	s_movk_i32 s6, 0x80
	v_cmp_lt_u32_e32 vcc, s6, v58
	v_add_u32_e32 v58, 1, v57
	v_not_b32_e32 v59, v57
	v_max_i32_e32 v58, v58, v59
	v_cndmask_b32_e32 v28, v28, v118, vcc
	v_cmp_gt_u32_e32 vcc, s74, v58
	v_add_u32_e32 v58, 2, v57
	v_sub_u32_e32 v59, -2, v57
	v_max_i32_e32 v58, v58, v59
	v_cndmask_b32_e32 v29, v118, v29, vcc
	v_cmp_gt_u32_e32 vcc, s74, v58
	v_add_u32_e32 v58, 3, v57
	v_sub_u32_e32 v57, -3, v57
	v_max_i32_e32 v57, v58, v57
	v_cndmask_b32_e32 v30, v118, v30, vcc
	v_cmp_gt_u32_e32 vcc, s74, v57
	v_sub_u32_e32 v57, v70, v56
	v_sub_u32_e32 v58, 0, v57
	v_max_i32_e32 v58, v57, v58
	v_cndmask_b32_e32 v31, v118, v31, vcc
	v_cmp_gt_u32_e32 vcc, s74, v58
	v_add_u32_e32 v58, 1, v57
	v_not_b32_e32 v59, v57
	v_max_i32_e32 v58, v58, v59
	v_cndmask_b32_e32 v32, v118, v32, vcc
	v_cmp_gt_u32_e32 vcc, s74, v58
	v_add_u32_e32 v58, 2, v57
	v_sub_u32_e32 v59, -2, v57
	v_max_i32_e32 v58, v58, v59
	v_cndmask_b32_e32 v33, v118, v33, vcc
	v_cmp_gt_u32_e32 vcc, s74, v58
	v_add_u32_e32 v58, 3, v57
	v_sub_u32_e32 v57, -3, v57
	v_max_i32_e32 v57, v58, v57
	v_cndmask_b32_e32 v34, v118, v34, vcc
	v_cmp_gt_u32_e32 vcc, s74, v57
	v_sub_u32_e32 v57, v71, v56
	v_sub_u32_e32 v58, 0, v57
	v_max_i32_e32 v58, v57, v58
	v_cndmask_b32_e32 v35, v118, v35, vcc
	v_cmp_gt_u32_e32 vcc, s74, v58
	v_add_u32_e32 v58, 1, v57
	v_not_b32_e32 v59, v57
	v_max_i32_e32 v58, v58, v59
	v_cndmask_b32_e32 v36, v118, v36, vcc
	v_cmp_gt_u32_e32 vcc, s74, v58
	v_add_u32_e32 v58, 2, v57
	v_sub_u32_e32 v59, -2, v57
	v_max_i32_e32 v58, v58, v59
	v_cndmask_b32_e32 v37, v118, v37, vcc
	v_cmp_gt_u32_e32 vcc, s74, v58
	v_add_u32_e32 v58, 3, v57
	v_sub_u32_e32 v57, -3, v57
	v_max_i32_e32 v57, v58, v57
	v_sub_u32_e32 v56, v72, v56
	v_cndmask_b32_e32 v38, v118, v38, vcc
	v_cmp_gt_u32_e32 vcc, s74, v57
	v_sub_u32_e32 v57, 0, v56
	v_max_i32_e32 v57, v56, v57
	v_cndmask_b32_e32 v39, v118, v39, vcc
	v_cmp_gt_u32_e32 vcc, s74, v57
	v_add_u32_e32 v57, 1, v56
	v_not_b32_e32 v58, v56
	v_max_i32_e32 v57, v57, v58
	v_cndmask_b32_e32 v40, v118, v40, vcc
	v_cmp_gt_u32_e32 vcc, s74, v57
	v_add_u32_e32 v57, 2, v56
	v_sub_u32_e32 v58, -2, v56
	v_max_i32_e32 v57, v57, v58
	v_cndmask_b32_e32 v41, v118, v41, vcc
	v_cmp_gt_u32_e32 vcc, s74, v57
	v_add_u32_e32 v57, 3, v56
	v_sub_u32_e32 v56, -3, v56
	v_max_i32_e32 v56, v57, v56
	v_cndmask_b32_e32 v42, v118, v42, vcc
	v_cmp_gt_u32_e32 vcc, s74, v56
	s_nop 1
	v_cndmask_b32_e32 v43, v118, v43, vcc
	s_branch .LBB0_870

.LBB0_985:
	s_andn2_saveexec_b64 s[0:1], s[0:1]
	s_cbranch_execz .LBB0_1003
	s_waitcnt vmcnt(16)
	s_mov_b32 s98, 0xaaaaaab
	v_mul_hi_u32 v78, v226, s98
	v_mul_u32_u24_e32 v79, 24, v78
	v_sub_u32_e32 v79, v226, v79
	v_lshlrev_b32_e32 v1, 5, v79
	v_and_b32_e32 v80, 7, v79
	v_mul_u32_u24_e32 v89, 0x480, v78
	v_lshl_add_u32 v89, v80, 4, v89
	v_cmp_gt_u32_e32 vcc, 16, v79
	v_mul_u32_u24_e32 v143, 0x480, v80
	v_lshl_add_u32 v143, v78, 4, v143
	v_mov_b32_e32 v78, 0x2400
	v_cndmask_b32_e32 v78, 0, v78, vcc
	v_add_u32_e32 v89, v89, v78
	v_cmp_gt_u32_e32 vcc, 8, v79
	v_mov_b32_e32 v78, 0x6c00
	v_mov_b32_e32 v80, 0x4800
	s_nop 0
	v_cndmask_b32_e32 v78, v78, v80, vcc
	v_add_u32_e32 v143, v143, v78
	s_mov_b32 s98, 0xbfb8aa3b
	s_mov_b32 s99, s98
	ds_read_b64 v[66:67], v1 offset:46848
	ds_read_b64 v[68:69], v1 offset:47616
	ds_read_b64 v[70:71], v1 offset:48384
	ds_read_b64 v[72:73], v1 offset:49152
	ds_read_b64 v[74:75], v1 offset:49920
	ds_read_b64 v[76:77], v1 offset:50688
	v_lshlrev_b32_e32 v78, 16, v18
	v_and_b32_e32 v79, 0xffff0000, v18
	v_lshlrev_b32_e32 v80, 16, v14
	v_and_b32_e32 v81, 0xffff0000, v14
	v_lshlrev_b32_e32 v82, 16, v26
	v_and_b32_e32 v83, 0xffff0000, v26
	v_lshlrev_b32_e32 v84, 16, v30
	v_and_b32_e32 v85, 0xffff0000, v30
	v_lshlrev_b32_e32 v144, 16, v34
	v_and_b32_e32 v145, 0xffff0000, v34
	v_lshlrev_b32_e32 v146, 16, v38
	v_and_b32_e32 v147, 0xffff0000, v38
	v_lshlrev_b32_e32 v148, 16, v42
	v_and_b32_e32 v149, 0xffff0000, v42
	v_lshlrev_b32_e32 v150, 16, v46
	v_and_b32_e32 v151, 0xffff0000, v46
	v_lshlrev_b32_e32 v152, 16, v50
	v_and_b32_e32 v153, 0xffff0000, v50
	v_lshlrev_b32_e32 v154, 16, v54
	v_and_b32_e32 v155, 0xffff0000, v54
	v_lshlrev_b32_e32 v156, 16, v58
	v_and_b32_e32 v157, 0xffff0000, v58
	v_lshlrev_b32_e32 v158, 16, v62
	v_and_b32_e32 v159, 0xffff0000, v62
	s_waitcnt lgkmcnt(0)
	v_pk_fma_f32 v[106:107], v[66:67], v[78:79], v[76:77]
	v_pk_fma_f32 v[106:107], v[68:69], v[80:81], v[106:107]
	v_pk_fma_f32 v[106:107], v[70:71], v[82:83], v[106:107]
	v_pk_fma_f32 v[106:107], v[72:73], v[84:85], v[106:107]
	v_pk_fma_f32 v[106:107], v[74:75], v[144:145], v[106:107]
	v_pk_mul_f32 v[242:243], v[106:107], s[98:99]
	v_exp_f32_e32 v242, v242
	v_exp_f32_e32 v243, v243
	v_pk_fma_f32 v[244:245], v[66:67], v[80:81], v[76:77]
	v_pk_add_f32 v[242:243], v[242:243], 1.0 op_sel_hi:[1,0]
	v_rcp_f32_e32 v242, v242
	v_rcp_f32_e32 v243, v243
	v_pk_fma_f32 v[244:245], v[68:69], v[82:83], v[244:245]
	v_pk_mul_f32 v[78:79], v[106:107], v[242:243]
	v_pk_fma_f32 v[244:245], v[70:71], v[84:85], v[244:245]
	v_pk_fma_f32 v[244:245], v[72:73], v[144:145], v[244:245]
	v_pk_fma_f32 v[244:245], v[74:75], v[146:147], v[244:245]
	v_pk_mul_f32 v[242:243], v[244:245], s[98:99]
	v_exp_f32_e32 v242, v242
	v_exp_f32_e32 v243, v243
	v_pk_fma_f32 v[106:107], v[66:67], v[82:83], v[76:77]
	v_pk_add_f32 v[242:243], v[242:243], 1.0 op_sel_hi:[1,0]
	v_rcp_f32_e32 v242, v242
	v_rcp_f32_e32 v243, v243
	v_pk_fma_f32 v[106:107], v[68:69], v[84:85], v[106:107]
	v_pk_mul_f32 v[80:81], v[244:245], v[242:243]
	v_pk_fma_f32 v[106:107], v[70:71], v[144:145], v[106:107]
	v_pk_fma_f32 v[106:107], v[72:73], v[146:147], v[106:107]
	v_pk_fma_f32 v[106:107], v[74:75], v[148:149], v[106:107]
	v_pk_mul_f32 v[242:243], v[106:107], s[98:99]
	v_exp_f32_e32 v242, v242
	v_exp_f32_e32 v243, v243
	v_pk_fma_f32 v[244:245], v[66:67], v[84:85], v[76:77]
	v_pk_add_f32 v[242:243], v[242:243], 1.0 op_sel_hi:[1,0]
	v_rcp_f32_e32 v242, v242
	v_rcp_f32_e32 v243, v243
	v_pk_fma_f32 v[244:245], v[68:69], v[144:145], v[244:245]
	v_pk_mul_f32 v[82:83], v[106:107], v[242:243]
	v_pk_fma_f32 v[244:245], v[70:71], v[146:147], v[244:245]
	v_pk_fma_f32 v[244:245], v[72:73], v[148:149], v[244:245]
	v_pk_fma_f32 v[244:245], v[74:75], v[150:151], v[244:245]
	v_pk_mul_f32 v[242:243], v[244:245], s[98:99]
	v_exp_f32_e32 v242, v242
	v_exp_f32_e32 v243, v243
	v_pk_fma_f32 v[106:107], v[66:67], v[144:145], v[76:77]
	v_pk_add_f32 v[242:243], v[242:243], 1.0 op_sel_hi:[1,0]
	v_rcp_f32_e32 v242, v242
	v_rcp_f32_e32 v243, v243
	v_pk_fma_f32 v[106:107], v[68:69], v[146:147], v[106:107]
	v_pk_mul_f32 v[84:85], v[244:245], v[242:243]
	v_pk_fma_f32 v[106:107], v[70:71], v[148:149], v[106:107]
	v_pk_fma_f32 v[106:107], v[72:73], v[150:151], v[106:107]
	v_pk_fma_f32 v[106:107], v[74:75], v[152:153], v[106:107]
	v_pk_mul_f32 v[242:243], v[106:107], s[98:99]
	v_exp_f32_e32 v242, v242
	v_exp_f32_e32 v243, v243
	v_pk_fma_f32 v[244:245], v[66:67], v[146:147], v[76:77]
	v_pk_add_f32 v[242:243], v[242:243], 1.0 op_sel_hi:[1,0]
	v_rcp_f32_e32 v242, v242
	v_rcp_f32_e32 v243, v243
	v_pk_fma_f32 v[244:245], v[68:69], v[148:149], v[244:245]
	v_pk_mul_f32 v[144:145], v[106:107], v[242:243]
	v_pk_fma_f32 v[244:245], v[70:71], v[150:151], v[244:245]
	v_pk_fma_f32 v[244:245], v[72:73], v[152:153], v[244:245]
	v_pk_fma_f32 v[244:245], v[74:75], v[154:155], v[244:245]
	v_pk_mul_f32 v[242:243], v[244:245], s[98:99]
	v_exp_f32_e32 v242, v242
	v_exp_f32_e32 v243, v243
	v_pk_fma_f32 v[106:107], v[66:67], v[148:149], v[76:77]
	v_pk_add_f32 v[242:243], v[242:243], 1.0 op_sel_hi:[1,0]
	v_rcp_f32_e32 v242, v242
	v_rcp_f32_e32 v243, v243
	v_pk_fma_f32 v[106:107], v[68:69], v[150:151], v[106:107]
	v_pk_mul_f32 v[146:147], v[244:245], v[242:243]
	v_pk_fma_f32 v[106:107], v[70:71], v[152:153], v[106:107]
	v_pk_fma_f32 v[106:107], v[72:73], v[154:155], v[106:107]
	v_pk_fma_f32 v[106:107], v[74:75], v[156:157], v[106:107]
	v_pk_mul_f32 v[242:243], v[106:107], s[98:99]
	v_exp_f32_e32 v242, v242
	v_exp_f32_e32 v243, v243
	v_pk_fma_f32 v[244:245], v[66:67], v[150:151], v[76:77]
	v_pk_add_f32 v[242:243], v[242:243], 1.0 op_sel_hi:[1,0]
	v_rcp_f32_e32 v242, v242
	v_rcp_f32_e32 v243, v243
	v_pk_fma_f32 v[244:245], v[68:69], v[152:153], v[244:245]
	v_pk_mul_f32 v[148:149], v[106:107], v[242:243]
	v_pk_fma_f32 v[244:245], v[70:71], v[154:155], v[244:245]
	v_pk_fma_f32 v[244:245], v[72:73], v[156:157], v[244:245]
	v_pk_fma_f32 v[244:245], v[74:75], v[158:159], v[244:245]
	v_pk_mul_f32 v[242:243], v[244:245], s[98:99]
	v_exp_f32_e32 v242, v242
	v_exp_f32_e32 v243, v243
	s_nop 0
	v_pk_add_f32 v[242:243], v[242:243], 1.0 op_sel_hi:[1,0]
	v_rcp_f32_e32 v242, v242
	v_rcp_f32_e32 v243, v243
	s_nop 0
	v_pk_mul_f32 v[150:151], v[244:245], v[242:243]
	s_and_saveexec_b64 s[58:59], s[8:9]
	s_cbranch_execz .LssdA0_r0
	v_cvt_pk_bf16_f32 v70, v78, v79
	v_cvt_pk_bf16_f32 v71, v80, v81
	ds_write2_b32 v89, v70, v71 offset0:0 offset1:36
	v_cvt_pk_bf16_f32 v70, v82, v83
	v_cvt_pk_bf16_f32 v71, v84, v85
	ds_write2_b32 v89, v70, v71 offset0:72 offset1:108
	v_cvt_pk_bf16_f32 v70, v144, v145
	v_cvt_pk_bf16_f32 v71, v146, v147
	ds_write2_b32 v89, v70, v71 offset0:144 offset1:180
	v_cvt_pk_bf16_f32 v70, v148, v149
	v_cvt_pk_bf16_f32 v71, v150, v151
	ds_write2_b32 v89, v70, v71 offset0:216 offset1:252
.LssdA0_r0:
	s_or_b64 exec, exec, s[58:59]
	s_and_saveexec_b64 s[58:59], s[10:11]
	s_cbranch_execz .LssdA0_t0
	v_cvt_pk_bf16_f32 v66, v78, v80
	v_cvt_pk_bf16_f32 v67, v82, v84
	v_cvt_pk_bf16_f32 v68, v144, v146
	v_cvt_pk_bf16_f32 v69, v148, v150
	ds_write_b128 v143, v[66:69] offset:0
	v_cvt_pk_bf16_f32 v66, v79, v81
	v_cvt_pk_bf16_f32 v67, v83, v85
	v_cvt_pk_bf16_f32 v68, v145, v147
	v_cvt_pk_bf16_f32 v69, v149, v151
	ds_write_b128 v143, v[66:69] offset:144
.LssdA0_t0:
	s_or_b64 exec, exec, s[58:59]
	ds_read_b64 v[66:67], v1 offset:46856
	ds_read_b64 v[68:69], v1 offset:47624
	ds_read_b64 v[70:71], v1 offset:48392
	ds_read_b64 v[72:73], v1 offset:49160
	ds_read_b64 v[74:75], v1 offset:49928
	ds_read_b64 v[76:77], v1 offset:50696
	v_lshlrev_b32_e32 v78, 16, v19
	v_and_b32_e32 v79, 0xffff0000, v19
	v_lshlrev_b32_e32 v80, 16, v15
	v_and_b32_e32 v81, 0xffff0000, v15
	v_lshlrev_b32_e32 v82, 16, v27
	v_and_b32_e32 v83, 0xffff0000, v27
	v_lshlrev_b32_e32 v84, 16, v31
	v_and_b32_e32 v85, 0xffff0000, v31
	v_lshlrev_b32_e32 v144, 16, v35
	v_and_b32_e32 v145, 0xffff0000, v35
	v_lshlrev_b32_e32 v146, 16, v39
	v_and_b32_e32 v147, 0xffff0000, v39
	v_lshlrev_b32_e32 v148, 16, v43
	v_and_b32_e32 v149, 0xffff0000, v43
	v_lshlrev_b32_e32 v150, 16, v47
	v_and_b32_e32 v151, 0xffff0000, v47
	v_lshlrev_b32_e32 v152, 16, v51
	v_and_b32_e32 v153, 0xffff0000, v51
	v_lshlrev_b32_e32 v154, 16, v55
	v_and_b32_e32 v155, 0xffff0000, v55
	v_lshlrev_b32_e32 v156, 16, v59
	v_and_b32_e32 v157, 0xffff0000, v59
	v_lshlrev_b32_e32 v158, 16, v63
	v_and_b32_e32 v159, 0xffff0000, v63
	s_waitcnt lgkmcnt(0)
	v_pk_fma_f32 v[106:107], v[66:67], v[78:79], v[76:77]
	v_pk_fma_f32 v[106:107], v[68:69], v[80:81], v[106:107]
	v_pk_fma_f32 v[106:107], v[70:71], v[82:83], v[106:107]
	v_pk_fma_f32 v[106:107], v[72:73], v[84:85], v[106:107]
	v_pk_fma_f32 v[106:107], v[74:75], v[144:145], v[106:107]
	v_pk_mul_f32 v[242:243], v[106:107], s[98:99]
	v_exp_f32_e32 v242, v242
	v_exp_f32_e32 v243, v243
	v_pk_fma_f32 v[244:245], v[66:67], v[80:81], v[76:77]
	v_pk_add_f32 v[242:243], v[242:243], 1.0 op_sel_hi:[1,0]
	v_rcp_f32_e32 v242, v242
	v_rcp_f32_e32 v243, v243
	v_pk_fma_f32 v[244:245], v[68:69], v[82:83], v[244:245]
	v_pk_mul_f32 v[78:79], v[106:107], v[242:243]
	v_pk_fma_f32 v[244:245], v[70:71], v[84:85], v[244:245]
	v_pk_fma_f32 v[244:245], v[72:73], v[144:145], v[244:245]
	v_pk_fma_f32 v[244:245], v[74:75], v[146:147], v[244:245]
	v_pk_mul_f32 v[242:243], v[244:245], s[98:99]
	v_exp_f32_e32 v242, v242
	v_exp_f32_e32 v243, v243
	v_pk_fma_f32 v[106:107], v[66:67], v[82:83], v[76:77]
	v_pk_add_f32 v[242:243], v[242:243], 1.0 op_sel_hi:[1,0]
	v_rcp_f32_e32 v242, v242
	v_rcp_f32_e32 v243, v243
	v_pk_fma_f32 v[106:107], v[68:69], v[84:85], v[106:107]
	v_pk_mul_f32 v[80:81], v[244:245], v[242:243]
	v_pk_fma_f32 v[106:107], v[70:71], v[144:145], v[106:107]
	v_pk_fma_f32 v[106:107], v[72:73], v[146:147], v[106:107]
	v_pk_fma_f32 v[106:107], v[74:75], v[148:149], v[106:107]
	v_pk_mul_f32 v[242:243], v[106:107], s[98:99]
	v_exp_f32_e32 v242, v242
	v_exp_f32_e32 v243, v243
	v_pk_fma_f32 v[244:245], v[66:67], v[84:85], v[76:77]
	v_pk_add_f32 v[242:243], v[242:243], 1.0 op_sel_hi:[1,0]
	v_rcp_f32_e32 v242, v242
	v_rcp_f32_e32 v243, v243
	v_pk_fma_f32 v[244:245], v[68:69], v[144:145], v[244:245]
	v_pk_mul_f32 v[82:83], v[106:107], v[242:243]
	v_pk_fma_f32 v[244:245], v[70:71], v[146:147], v[244:245]
	v_pk_fma_f32 v[244:245], v[72:73], v[148:149], v[244:245]
	v_pk_fma_f32 v[244:245], v[74:75], v[150:151], v[244:245]
	v_pk_mul_f32 v[242:243], v[244:245], s[98:99]
	v_exp_f32_e32 v242, v242
	v_exp_f32_e32 v243, v243
	v_pk_fma_f32 v[106:107], v[66:67], v[144:145], v[76:77]
	v_pk_add_f32 v[242:243], v[242:243], 1.0 op_sel_hi:[1,0]
	v_rcp_f32_e32 v242, v242
	v_rcp_f32_e32 v243, v243
	v_pk_fma_f32 v[106:107], v[68:69], v[146:147], v[106:107]
	v_pk_mul_f32 v[84:85], v[244:245], v[242:243]
	v_pk_fma_f32 v[106:107], v[70:71], v[148:149], v[106:107]
	v_pk_fma_f32 v[106:107], v[72:73], v[150:151], v[106:107]
	v_pk_fma_f32 v[106:107], v[74:75], v[152:153], v[106:107]
	v_pk_mul_f32 v[242:243], v[106:107], s[98:99]
	v_exp_f32_e32 v242, v242
	v_exp_f32_e32 v243, v243
	v_pk_fma_f32 v[244:245], v[66:67], v[146:147], v[76:77]
	v_pk_add_f32 v[242:243], v[242:243], 1.0 op_sel_hi:[1,0]
	v_rcp_f32_e32 v242, v242
	v_rcp_f32_e32 v243, v243
	v_pk_fma_f32 v[244:245], v[68:69], v[148:149], v[244:245]
	v_pk_mul_f32 v[144:145], v[106:107], v[242:243]
	v_pk_fma_f32 v[244:245], v[70:71], v[150:151], v[244:245]
	v_pk_fma_f32 v[244:245], v[72:73], v[152:153], v[244:245]
	v_pk_fma_f32 v[244:245], v[74:75], v[154:155], v[244:245]
	v_pk_mul_f32 v[242:243], v[244:245], s[98:99]
	v_exp_f32_e32 v242, v242
	v_exp_f32_e32 v243, v243
	v_pk_fma_f32 v[106:107], v[66:67], v[148:149], v[76:77]
	v_pk_add_f32 v[242:243], v[242:243], 1.0 op_sel_hi:[1,0]
	v_rcp_f32_e32 v242, v242
	v_rcp_f32_e32 v243, v243
	v_pk_fma_f32 v[106:107], v[68:69], v[150:151], v[106:107]
	v_pk_mul_f32 v[146:147], v[244:245], v[242:243]
	v_pk_fma_f32 v[106:107], v[70:71], v[152:153], v[106:107]
	v_pk_fma_f32 v[106:107], v[72:73], v[154:155], v[106:107]
	v_pk_fma_f32 v[106:107], v[74:75], v[156:157], v[106:107]
	v_pk_mul_f32 v[242:243], v[106:107], s[98:99]
	v_exp_f32_e32 v242, v242
	v_exp_f32_e32 v243, v243
	v_pk_fma_f32 v[244:245], v[66:67], v[150:151], v[76:77]
	v_pk_add_f32 v[242:243], v[242:243], 1.0 op_sel_hi:[1,0]
	v_rcp_f32_e32 v242, v242
	v_rcp_f32_e32 v243, v243
	v_pk_fma_f32 v[244:245], v[68:69], v[152:153], v[244:245]
	v_pk_mul_f32 v[148:149], v[106:107], v[242:243]
	v_pk_fma_f32 v[244:245], v[70:71], v[154:155], v[244:245]
	v_pk_fma_f32 v[244:245], v[72:73], v[156:157], v[244:245]
	v_pk_fma_f32 v[244:245], v[74:75], v[158:159], v[244:245]
	v_pk_mul_f32 v[242:243], v[244:245], s[98:99]
	v_exp_f32_e32 v242, v242
	v_exp_f32_e32 v243, v243
	s_nop 0
	v_pk_add_f32 v[242:243], v[242:243], 1.0 op_sel_hi:[1,0]
	v_rcp_f32_e32 v242, v242
	v_rcp_f32_e32 v243, v243
	s_nop 0
	v_pk_mul_f32 v[150:151], v[244:245], v[242:243]
	s_and_saveexec_b64 s[58:59], s[8:9]
	s_cbranch_execz .LssdA0_r1
	v_cvt_pk_bf16_f32 v70, v78, v79
	v_cvt_pk_bf16_f32 v71, v80, v81
	ds_write2_b32 v89, v70, v71 offset0:1 offset1:37
	v_cvt_pk_bf16_f32 v70, v82, v83
	v_cvt_pk_bf16_f32 v71, v84, v85
	ds_write2_b32 v89, v70, v71 offset0:73 offset1:109
	v_cvt_pk_bf16_f32 v70, v144, v145
	v_cvt_pk_bf16_f32 v71, v146, v147
	ds_write2_b32 v89, v70, v71 offset0:145 offset1:181
	v_cvt_pk_bf16_f32 v70, v148, v149
	v_cvt_pk_bf16_f32 v71, v150, v151
	ds_write2_b32 v89, v70, v71 offset0:217 offset1:253
.LssdA0_r1:
	s_or_b64 exec, exec, s[58:59]
	s_and_saveexec_b64 s[58:59], s[10:11]
	s_cbranch_execz .LssdA0_t1
	v_cvt_pk_bf16_f32 v66, v78, v80
	v_cvt_pk_bf16_f32 v67, v82, v84
	v_cvt_pk_bf16_f32 v68, v144, v146
	v_cvt_pk_bf16_f32 v69, v148, v150
	ds_write_b128 v143, v[66:69] offset:288
	v_cvt_pk_bf16_f32 v66, v79, v81
	v_cvt_pk_bf16_f32 v67, v83, v85
	v_cvt_pk_bf16_f32 v68, v145, v147
	v_cvt_pk_bf16_f32 v69, v149, v151
	ds_write_b128 v143, v[66:69] offset:432
.LssdA0_t1:
	s_or_b64 exec, exec, s[58:59]
	ds_read_b64 v[66:67], v1 offset:46864
	ds_read_b64 v[68:69], v1 offset:47632
	ds_read_b64 v[70:71], v1 offset:48400
	ds_read_b64 v[72:73], v1 offset:49168
	ds_read_b64 v[74:75], v1 offset:49936
	ds_read_b64 v[76:77], v1 offset:50704
	v_lshlrev_b32_e32 v78, 16, v20
	v_and_b32_e32 v79, 0xffff0000, v20
	v_lshlrev_b32_e32 v80, 16, v16
	v_and_b32_e32 v81, 0xffff0000, v16
	v_lshlrev_b32_e32 v82, 16, v28
	v_and_b32_e32 v83, 0xffff0000, v28
	v_lshlrev_b32_e32 v84, 16, v32
	v_and_b32_e32 v85, 0xffff0000, v32
	v_lshlrev_b32_e32 v144, 16, v36
	v_and_b32_e32 v145, 0xffff0000, v36
	v_lshlrev_b32_e32 v146, 16, v40
	v_and_b32_e32 v147, 0xffff0000, v40
	v_lshlrev_b32_e32 v148, 16, v44
	v_and_b32_e32 v149, 0xffff0000, v44
	v_lshlrev_b32_e32 v150, 16, v48
	v_and_b32_e32 v151, 0xffff0000, v48
	v_lshlrev_b32_e32 v152, 16, v52
	v_and_b32_e32 v153, 0xffff0000, v52
	v_lshlrev_b32_e32 v154, 16, v56
	v_and_b32_e32 v155, 0xffff0000, v56
	v_lshlrev_b32_e32 v156, 16, v60
	v_and_b32_e32 v157, 0xffff0000, v60
	v_lshlrev_b32_e32 v158, 16, v64
	v_and_b32_e32 v159, 0xffff0000, v64
	s_waitcnt lgkmcnt(0)
	v_pk_fma_f32 v[106:107], v[66:67], v[78:79], v[76:77]
	v_pk_fma_f32 v[106:107], v[68:69], v[80:81], v[106:107]
	v_pk_fma_f32 v[106:107], v[70:71], v[82:83], v[106:107]
	v_pk_fma_f32 v[106:107], v[72:73], v[84:85], v[106:107]
	v_pk_fma_f32 v[106:107], v[74:75], v[144:145], v[106:107]
	v_pk_mul_f32 v[242:243], v[106:107], s[98:99]
	v_exp_f32_e32 v242, v242
	v_exp_f32_e32 v243, v243
	v_pk_fma_f32 v[244:245], v[66:67], v[80:81], v[76:77]
	v_pk_add_f32 v[242:243], v[242:243], 1.0 op_sel_hi:[1,0]
	v_rcp_f32_e32 v242, v242
	v_rcp_f32_e32 v243, v243
	v_pk_fma_f32 v[244:245], v[68:69], v[82:83], v[244:245]
	v_pk_mul_f32 v[78:79], v[106:107], v[242:243]
	v_pk_fma_f32 v[244:245], v[70:71], v[84:85], v[244:245]
	v_pk_fma_f32 v[244:245], v[72:73], v[144:145], v[244:245]
	v_pk_fma_f32 v[244:245], v[74:75], v[146:147], v[244:245]
	v_pk_mul_f32 v[242:243], v[244:245], s[98:99]
	v_exp_f32_e32 v242, v242
	v_exp_f32_e32 v243, v243
	v_pk_fma_f32 v[106:107], v[66:67], v[82:83], v[76:77]
	v_pk_add_f32 v[242:243], v[242:243], 1.0 op_sel_hi:[1,0]
	v_rcp_f32_e32 v242, v242
	v_rcp_f32_e32 v243, v243
	v_pk_fma_f32 v[106:107], v[68:69], v[84:85], v[106:107]
	v_pk_mul_f32 v[80:81], v[244:245], v[242:243]
	v_pk_fma_f32 v[106:107], v[70:71], v[144:145], v[106:107]
	v_pk_fma_f32 v[106:107], v[72:73], v[146:147], v[106:107]
	v_pk_fma_f32 v[106:107], v[74:75], v[148:149], v[106:107]
	v_pk_mul_f32 v[242:243], v[106:107], s[98:99]
	v_exp_f32_e32 v242, v242
	v_exp_f32_e32 v243, v243
	v_pk_fma_f32 v[244:245], v[66:67], v[84:85], v[76:77]
	v_pk_add_f32 v[242:243], v[242:243], 1.0 op_sel_hi:[1,0]
	v_rcp_f32_e32 v242, v242
	v_rcp_f32_e32 v243, v243
	v_pk_fma_f32 v[244:245], v[68:69], v[144:145], v[244:245]
	v_pk_mul_f32 v[82:83], v[106:107], v[242:243]
	v_pk_fma_f32 v[244:245], v[70:71], v[146:147], v[244:245]
	v_pk_fma_f32 v[244:245], v[72:73], v[148:149], v[244:245]
	v_pk_fma_f32 v[244:245], v[74:75], v[150:151], v[244:245]
	v_pk_mul_f32 v[242:243], v[244:245], s[98:99]
	v_exp_f32_e32 v242, v242
	v_exp_f32_e32 v243, v243
	v_pk_fma_f32 v[106:107], v[66:67], v[144:145], v[76:77]
	v_pk_add_f32 v[242:243], v[242:243], 1.0 op_sel_hi:[1,0]
	v_rcp_f32_e32 v242, v242
	v_rcp_f32_e32 v243, v243
	v_pk_fma_f32 v[106:107], v[68:69], v[146:147], v[106:107]
	v_pk_mul_f32 v[84:85], v[244:245], v[242:243]
	v_pk_fma_f32 v[106:107], v[70:71], v[148:149], v[106:107]
	v_pk_fma_f32 v[106:107], v[72:73], v[150:151], v[106:107]
	v_pk_fma_f32 v[106:107], v[74:75], v[152:153], v[106:107]
	v_pk_mul_f32 v[242:243], v[106:107], s[98:99]
	v_exp_f32_e32 v242, v242
	v_exp_f32_e32 v243, v243
	v_pk_fma_f32 v[244:245], v[66:67], v[146:147], v[76:77]
	v_pk_add_f32 v[242:243], v[242:243], 1.0 op_sel_hi:[1,0]
	v_rcp_f32_e32 v242, v242
	v_rcp_f32_e32 v243, v243
	v_pk_fma_f32 v[244:245], v[68:69], v[148:149], v[244:245]
	v_pk_mul_f32 v[144:145], v[106:107], v[242:243]
	v_pk_fma_f32 v[244:245], v[70:71], v[150:151], v[244:245]
	v_pk_fma_f32 v[244:245], v[72:73], v[152:153], v[244:245]
	v_pk_fma_f32 v[244:245], v[74:75], v[154:155], v[244:245]
	v_pk_mul_f32 v[242:243], v[244:245], s[98:99]
	v_exp_f32_e32 v242, v242
	v_exp_f32_e32 v243, v243
	v_pk_fma_f32 v[106:107], v[66:67], v[148:149], v[76:77]
	v_pk_add_f32 v[242:243], v[242:243], 1.0 op_sel_hi:[1,0]
	v_rcp_f32_e32 v242, v242
	v_rcp_f32_e32 v243, v243
	v_pk_fma_f32 v[106:107], v[68:69], v[150:151], v[106:107]
	v_pk_mul_f32 v[146:147], v[244:245], v[242:243]
	v_pk_fma_f32 v[106:107], v[70:71], v[152:153], v[106:107]
	v_pk_fma_f32 v[106:107], v[72:73], v[154:155], v[106:107]
	v_pk_fma_f32 v[106:107], v[74:75], v[156:157], v[106:107]
	v_pk_mul_f32 v[242:243], v[106:107], s[98:99]
	v_exp_f32_e32 v242, v242
	v_exp_f32_e32 v243, v243
	v_pk_fma_f32 v[244:245], v[66:67], v[150:151], v[76:77]
	v_pk_add_f32 v[242:243], v[242:243], 1.0 op_sel_hi:[1,0]
	v_rcp_f32_e32 v242, v242
	v_rcp_f32_e32 v243, v243
	v_pk_fma_f32 v[244:245], v[68:69], v[152:153], v[244:245]
	v_pk_mul_f32 v[148:149], v[106:107], v[242:243]
	v_pk_fma_f32 v[244:245], v[70:71], v[154:155], v[244:245]
	v_pk_fma_f32 v[244:245], v[72:73], v[156:157], v[244:245]
	v_pk_fma_f32 v[244:245], v[74:75], v[158:159], v[244:245]
	v_pk_mul_f32 v[242:243], v[244:245], s[98:99]
	v_exp_f32_e32 v242, v242
	v_exp_f32_e32 v243, v243
	s_nop 0
	v_pk_add_f32 v[242:243], v[242:243], 1.0 op_sel_hi:[1,0]
	v_rcp_f32_e32 v242, v242
	v_rcp_f32_e32 v243, v243
	s_nop 0
	v_pk_mul_f32 v[150:151], v[244:245], v[242:243]
	s_and_saveexec_b64 s[58:59], s[8:9]
	s_cbranch_execz .LssdA0_r2
	v_cvt_pk_bf16_f32 v70, v78, v79
	v_cvt_pk_bf16_f32 v71, v80, v81
	ds_write2_b32 v89, v70, v71 offset0:2 offset1:38
	v_cvt_pk_bf16_f32 v70, v82, v83
	v_cvt_pk_bf16_f32 v71, v84, v85
	ds_write2_b32 v89, v70, v71 offset0:74 offset1:110
	v_cvt_pk_bf16_f32 v70, v144, v145
	v_cvt_pk_bf16_f32 v71, v146, v147
	ds_write2_b32 v89, v70, v71 offset0:146 offset1:182
	v_cvt_pk_bf16_f32 v70, v148, v149
	v_cvt_pk_bf16_f32 v71, v150, v151
	ds_write2_b32 v89, v70, v71 offset0:218 offset1:254
.LssdA0_r2:
	s_or_b64 exec, exec, s[58:59]
	s_and_saveexec_b64 s[58:59], s[10:11]
	s_cbranch_execz .LssdA0_t2
	v_cvt_pk_bf16_f32 v66, v78, v80
	v_cvt_pk_bf16_f32 v67, v82, v84
	v_cvt_pk_bf16_f32 v68, v144, v146
	v_cvt_pk_bf16_f32 v69, v148, v150
	ds_write_b128 v143, v[66:69] offset:576
	v_cvt_pk_bf16_f32 v66, v79, v81
	v_cvt_pk_bf16_f32 v67, v83, v85
	v_cvt_pk_bf16_f32 v68, v145, v147
	v_cvt_pk_bf16_f32 v69, v149, v151
	ds_write_b128 v143, v[66:69] offset:720
.LssdA0_t2:
	s_or_b64 exec, exec, s[58:59]
	ds_read_b64 v[66:67], v1 offset:46872
	ds_read_b64 v[68:69], v1 offset:47640
	ds_read_b64 v[70:71], v1 offset:48408
	ds_read_b64 v[72:73], v1 offset:49176
	ds_read_b64 v[74:75], v1 offset:49944
	ds_read_b64 v[76:77], v1 offset:50712
	v_lshlrev_b32_e32 v78, 16, v21
	v_and_b32_e32 v79, 0xffff0000, v21
	v_lshlrev_b32_e32 v80, 16, v17
	v_and_b32_e32 v81, 0xffff0000, v17
	v_lshlrev_b32_e32 v82, 16, v29
	v_and_b32_e32 v83, 0xffff0000, v29
	v_lshlrev_b32_e32 v84, 16, v33
	v_and_b32_e32 v85, 0xffff0000, v33
	v_lshlrev_b32_e32 v144, 16, v37
	v_and_b32_e32 v145, 0xffff0000, v37
	v_lshlrev_b32_e32 v146, 16, v41
	v_and_b32_e32 v147, 0xffff0000, v41
	v_lshlrev_b32_e32 v148, 16, v45
	v_and_b32_e32 v149, 0xffff0000, v45
	v_lshlrev_b32_e32 v150, 16, v49
	v_and_b32_e32 v151, 0xffff0000, v49
	v_lshlrev_b32_e32 v152, 16, v53
	v_and_b32_e32 v153, 0xffff0000, v53
	v_lshlrev_b32_e32 v154, 16, v57
	v_and_b32_e32 v155, 0xffff0000, v57
	v_lshlrev_b32_e32 v156, 16, v61
	v_and_b32_e32 v157, 0xffff0000, v61
	v_lshlrev_b32_e32 v158, 16, v65
	v_and_b32_e32 v159, 0xffff0000, v65
	s_waitcnt lgkmcnt(0)
	v_pk_fma_f32 v[106:107], v[66:67], v[78:79], v[76:77]
	v_pk_fma_f32 v[106:107], v[68:69], v[80:81], v[106:107]
	v_pk_fma_f32 v[106:107], v[70:71], v[82:83], v[106:107]
	v_pk_fma_f32 v[106:107], v[72:73], v[84:85], v[106:107]
	v_pk_fma_f32 v[106:107], v[74:75], v[144:145], v[106:107]
	v_pk_mul_f32 v[242:243], v[106:107], s[98:99]
	v_exp_f32_e32 v242, v242
	v_exp_f32_e32 v243, v243
	v_pk_fma_f32 v[244:245], v[66:67], v[80:81], v[76:77]
	v_pk_add_f32 v[242:243], v[242:243], 1.0 op_sel_hi:[1,0]
	v_rcp_f32_e32 v242, v242
	v_rcp_f32_e32 v243, v243
	v_pk_fma_f32 v[244:245], v[68:69], v[82:83], v[244:245]
	v_pk_mul_f32 v[78:79], v[106:107], v[242:243]
	v_pk_fma_f32 v[244:245], v[70:71], v[84:85], v[244:245]
	v_pk_fma_f32 v[244:245], v[72:73], v[144:145], v[244:245]
	v_pk_fma_f32 v[244:245], v[74:75], v[146:147], v[244:245]
	v_pk_mul_f32 v[242:243], v[244:245], s[98:99]
	v_exp_f32_e32 v242, v242
	v_exp_f32_e32 v243, v243
	v_pk_fma_f32 v[106:107], v[66:67], v[82:83], v[76:77]
	v_pk_add_f32 v[242:243], v[242:243], 1.0 op_sel_hi:[1,0]
	v_rcp_f32_e32 v242, v242
	v_rcp_f32_e32 v243, v243
	v_pk_fma_f32 v[106:107], v[68:69], v[84:85], v[106:107]
	v_pk_mul_f32 v[80:81], v[244:245], v[242:243]
	v_pk_fma_f32 v[106:107], v[70:71], v[144:145], v[106:107]
	v_pk_fma_f32 v[106:107], v[72:73], v[146:147], v[106:107]
	v_pk_fma_f32 v[106:107], v[74:75], v[148:149], v[106:107]
	v_pk_mul_f32 v[242:243], v[106:107], s[98:99]
	v_exp_f32_e32 v242, v242
	v_exp_f32_e32 v243, v243
	v_pk_fma_f32 v[244:245], v[66:67], v[84:85], v[76:77]
	v_pk_add_f32 v[242:243], v[242:243], 1.0 op_sel_hi:[1,0]
	v_rcp_f32_e32 v242, v242
	v_rcp_f32_e32 v243, v243
	v_pk_fma_f32 v[244:245], v[68:69], v[144:145], v[244:245]
	v_pk_mul_f32 v[82:83], v[106:107], v[242:243]
	v_pk_fma_f32 v[244:245], v[70:71], v[146:147], v[244:245]
	v_pk_fma_f32 v[244:245], v[72:73], v[148:149], v[244:245]
	v_pk_fma_f32 v[244:245], v[74:75], v[150:151], v[244:245]
	v_pk_mul_f32 v[242:243], v[244:245], s[98:99]
	v_exp_f32_e32 v242, v242
	v_exp_f32_e32 v243, v243
	v_pk_fma_f32 v[106:107], v[66:67], v[144:145], v[76:77]
	v_pk_add_f32 v[242:243], v[242:243], 1.0 op_sel_hi:[1,0]
	v_rcp_f32_e32 v242, v242
	v_rcp_f32_e32 v243, v243
	v_pk_fma_f32 v[106:107], v[68:69], v[146:147], v[106:107]
	v_pk_mul_f32 v[84:85], v[244:245], v[242:243]
	v_pk_fma_f32 v[106:107], v[70:71], v[148:149], v[106:107]
	v_pk_fma_f32 v[106:107], v[72:73], v[150:151], v[106:107]
	v_pk_fma_f32 v[106:107], v[74:75], v[152:153], v[106:107]
	v_pk_mul_f32 v[242:243], v[106:107], s[98:99]
	v_exp_f32_e32 v242, v242
	v_exp_f32_e32 v243, v243
	v_pk_fma_f32 v[244:245], v[66:67], v[146:147], v[76:77]
	v_pk_add_f32 v[242:243], v[242:243], 1.0 op_sel_hi:[1,0]
	v_rcp_f32_e32 v242, v242
	v_rcp_f32_e32 v243, v243
	v_pk_fma_f32 v[244:245], v[68:69], v[148:149], v[244:245]
	v_pk_mul_f32 v[144:145], v[106:107], v[242:243]
	v_pk_fma_f32 v[244:245], v[70:71], v[150:151], v[244:245]
	v_pk_fma_f32 v[244:245], v[72:73], v[152:153], v[244:245]
	v_pk_fma_f32 v[244:245], v[74:75], v[154:155], v[244:245]
	v_pk_mul_f32 v[242:243], v[244:245], s[98:99]
	v_exp_f32_e32 v242, v242
	v_exp_f32_e32 v243, v243
	v_pk_fma_f32 v[106:107], v[66:67], v[148:149], v[76:77]
	v_pk_add_f32 v[242:243], v[242:243], 1.0 op_sel_hi:[1,0]
	v_rcp_f32_e32 v242, v242
	v_rcp_f32_e32 v243, v243
	v_pk_fma_f32 v[106:107], v[68:69], v[150:151], v[106:107]
	v_pk_mul_f32 v[146:147], v[244:245], v[242:243]
	v_pk_fma_f32 v[106:107], v[70:71], v[152:153], v[106:107]
	v_pk_fma_f32 v[106:107], v[72:73], v[154:155], v[106:107]
	v_pk_fma_f32 v[106:107], v[74:75], v[156:157], v[106:107]
	v_pk_mul_f32 v[242:243], v[106:107], s[98:99]
	v_exp_f32_e32 v242, v242
	v_exp_f32_e32 v243, v243
	v_pk_fma_f32 v[244:245], v[66:67], v[150:151], v[76:77]
	v_pk_add_f32 v[242:243], v[242:243], 1.0 op_sel_hi:[1,0]
	v_rcp_f32_e32 v242, v242
	v_rcp_f32_e32 v243, v243
	v_pk_fma_f32 v[244:245], v[68:69], v[152:153], v[244:245]
	v_pk_mul_f32 v[148:149], v[106:107], v[242:243]
	v_pk_fma_f32 v[244:245], v[70:71], v[154:155], v[244:245]
	v_pk_fma_f32 v[244:245], v[72:73], v[156:157], v[244:245]
	v_pk_fma_f32 v[244:245], v[74:75], v[158:159], v[244:245]
	v_pk_mul_f32 v[242:243], v[244:245], s[98:99]
	v_exp_f32_e32 v242, v242
	v_exp_f32_e32 v243, v243
	s_nop 0
	v_pk_add_f32 v[242:243], v[242:243], 1.0 op_sel_hi:[1,0]
	v_rcp_f32_e32 v242, v242
	v_rcp_f32_e32 v243, v243
	s_nop 0
	v_pk_mul_f32 v[150:151], v[244:245], v[242:243]
	s_and_saveexec_b64 s[58:59], s[8:9]
	s_cbranch_execz .LssdA0_r3
	v_cvt_pk_bf16_f32 v70, v78, v79
	v_cvt_pk_bf16_f32 v71, v80, v81
	ds_write2_b32 v89, v70, v71 offset0:3 offset1:39
	v_cvt_pk_bf16_f32 v70, v82, v83
	v_cvt_pk_bf16_f32 v71, v84, v85
	ds_write2_b32 v89, v70, v71 offset0:75 offset1:111
	v_cvt_pk_bf16_f32 v70, v144, v145
	v_cvt_pk_bf16_f32 v71, v146, v147
	ds_write2_b32 v89, v70, v71 offset0:147 offset1:183
	v_cvt_pk_bf16_f32 v70, v148, v149
	v_cvt_pk_bf16_f32 v71, v150, v151
	ds_write2_b32 v89, v70, v71 offset0:219 offset1:255
.LssdA0_r3:
	s_or_b64 exec, exec, s[58:59]
	s_and_saveexec_b64 s[58:59], s[10:11]
	s_cbranch_execz .LssdA0_t3
	v_cvt_pk_bf16_f32 v66, v78, v80
	v_cvt_pk_bf16_f32 v67, v82, v84
	v_cvt_pk_bf16_f32 v68, v144, v146
	v_cvt_pk_bf16_f32 v69, v148, v150
	ds_write_b128 v143, v[66:69] offset:864
	v_cvt_pk_bf16_f32 v66, v79, v81
	v_cvt_pk_bf16_f32 v67, v83, v85
	v_cvt_pk_bf16_f32 v68, v145, v147
	v_cvt_pk_bf16_f32 v69, v149, v151
	ds_write_b128 v143, v[66:69] offset:1008

.LBB0_2375:
	s_waitcnt vmcnt(0)
	v_cvt_pk_bf16_f32 v31, v30, v31
	v_cvt_pk_bf16_f32 v30, v28, v29
	v_cvt_pk_bf16_f32 v29, v38, v39
	v_cvt_pk_bf16_f32 v28, v36, v37
	ds_write_b128 v76, v[28:31] offset:16
	s_cmp_lg_u64 s[12:13], 0
	s_cbranch_scc0 .Lapf1_c
	v_add_u32_e32 v242, s25, v66
	v_add_u32_e32 v242, 64, v242
	v_mad_i64_i32 v[242:243], s[100:101], v242, s86, v[52:53]
	global_load_dword v244, v[242:243], off offset:1024
	global_load_dword v245, v[242:243], off offset:768
	s_branch .Lapf1_d
.Lapf1_c:
	s_cmp_lt_u32 s25, 0xc0
	s_cbranch_scc0 .Lapf1_d
	v_add_u32_e32 v242, s25, v65
	v_add_u32_e32 v242, 64, v242
	v_ashrrev_i32_e32 v243, 31, v242
	v_lshlrev_b64 v[242:243], 9, v[242:243]
	v_lshl_add_u64 v[244:245], v[48:49], 0, v[242:243]
	v_lshl_add_u64 v[242:243], v[50:51], 0, v[242:243]
	global_load_dword v244, v[244:245], off
	global_load_dword v242, v[242:243], off
.Lapf1_d:
	s_waitcnt lgkmcnt(0)
	s_barrier
	ds_read_b128 v[28:31], v77
	ds_read_b128 v[32:35], v77 offset:64
	s_waitcnt lgkmcnt(1)
	v_mfma_f32_16x16x32_bf16 v[28:31], v[4:7], v[28:31], 0
	s_and_b64 s[6:7], s[0:1], s[12:13]
	s_andn2_b64 vcc, exec, s[6:7]
	s_waitcnt lgkmcnt(0)
	v_mfma_f32_16x16x32_bf16 v[28:31], v[8:11], v[32:35], v[28:31]
	ds_read_b128 v[32:35], v77 offset:2304
	ds_read_b128 v[36:39], v77 offset:2368
	s_waitcnt lgkmcnt(1)
	v_mfma_f32_16x16x32_bf16 v[32:35], v[4:7], v[32:35], 0
	s_waitcnt lgkmcnt(0)
	v_mfma_f32_16x16x32_bf16 v[32:35], v[8:11], v[36:39], v[32:35]
	ds_read_b128 v[36:39], v77 offset:4608
	ds_read_b128 v[40:43], v77 offset:4672
	s_waitcnt lgkmcnt(1)
	v_mfma_f32_16x16x32_bf16 v[36:39], v[4:7], v[36:39], 0
	s_waitcnt lgkmcnt(0)
	v_mfma_f32_16x16x32_bf16 v[36:39], v[8:11], v[40:43], v[36:39]
	ds_read_b128 v[40:43], v77 offset:6912
	ds_read_b128 v[56:59], v77 offset:6976
	s_waitcnt lgkmcnt(1)
	v_mfma_f32_16x16x32_bf16 v[40:43], v[4:7], v[40:43], 0
	s_waitcnt lgkmcnt(0)
	v_mfma_f32_16x16x32_bf16 v[40:43], v[8:11], v[56:59], v[40:43]
	s_cbranch_vccnz .LBB0_2356
	v_add_u32_e32 v56, s25, v45
	v_sub_u32_e32 v57, v69, v56
	v_sub_u32_e32 v58, 0, v57
	v_max_i32_e32 v58, v57, v58
	s_movk_i32 s6, 0x80
	v_cmp_lt_u32_e32 vcc, s6, v58
	v_add_u32_e32 v58, 1, v57
	v_not_b32_e32 v59, v57
	v_max_i32_e32 v58, v58, v59
	v_cndmask_b32_e32 v28, v28, v118, vcc
	v_cmp_gt_u32_e32 vcc, s70, v58
	v_add_u32_e32 v58, 2, v57
	v_sub_u32_e32 v59, -2, v57
	v_max_i32_e32 v58, v58, v59
	v_cndmask_b32_e32 v29, v118, v29, vcc
	v_cmp_gt_u32_e32 vcc, s70, v58
	v_add_u32_e32 v58, 3, v57
	v_sub_u32_e32 v57, -3, v57
	v_max_i32_e32 v57, v58, v57
	v_cndmask_b32_e32 v30, v118, v30, vcc
	v_cmp_gt_u32_e32 vcc, s70, v57
	v_sub_u32_e32 v57, v70, v56
	v_sub_u32_e32 v58, 0, v57
	v_max_i32_e32 v58, v57, v58
	v_cndmask_b32_e32 v31, v118, v31, vcc
	v_cmp_gt_u32_e32 vcc, s70, v58
	v_add_u32_e32 v58, 1, v57
	v_not_b32_e32 v59, v57
	v_max_i32_e32 v58, v58, v59
	v_cndmask_b32_e32 v32, v118, v32, vcc
	v_cmp_gt_u32_e32 vcc, s70, v58
	v_add_u32_e32 v58, 2, v57
	v_sub_u32_e32 v59, -2, v57
	v_max_i32_e32 v58, v58, v59
	v_cndmask_b32_e32 v33, v118, v33, vcc
	v_cmp_gt_u32_e32 vcc, s70, v58
	v_add_u32_e32 v58, 3, v57
	v_sub_u32_e32 v57, -3, v57
	v_max_i32_e32 v57, v58, v57
	v_cndmask_b32_e32 v34, v118, v34, vcc
	v_cmp_gt_u32_e32 vcc, s70, v57
	v_sub_u32_e32 v57, v71, v56
	v_sub_u32_e32 v58, 0, v57
	v_max_i32_e32 v58, v57, v58
	v_cndmask_b32_e32 v35, v118, v35, vcc
	v_cmp_gt_u32_e32 vcc, s70, v58
	v_add_u32_e32 v58, 1, v57
	v_not_b32_e32 v59, v57
	v_max_i32_e32 v58, v58, v59
	v_cndmask_b32_e32 v36, v118, v36, vcc
	v_cmp_gt_u32_e32 vcc, s70, v58
	v_add_u32_e32 v58, 2, v57
	v_sub_u32_e32 v59, -2, v57
	v_max_i32_e32 v58, v58, v59
	v_cndmask_b32_e32 v37, v118, v37, vcc
	v_cmp_gt_u32_e32 vcc, s70, v58
	v_add_u32_e32 v58, 3, v57
	v_sub_u32_e32 v57, -3, v57
	v_max_i32_e32 v57, v58, v57
	v_sub_u32_e32 v56, v72, v56
	v_cndmask_b32_e32 v38, v118, v38, vcc
	v_cmp_gt_u32_e32 vcc, s70, v57
	v_sub_u32_e32 v57, 0, v56
	v_max_i32_e32 v57, v56, v57
	v_cndmask_b32_e32 v39, v118, v39, vcc
	v_cmp_gt_u32_e32 vcc, s70, v57
	v_add_u32_e32 v57, 1, v56
	v_not_b32_e32 v58, v56
	v_max_i32_e32 v57, v57, v58
	v_cndmask_b32_e32 v40, v118, v40, vcc
	v_cmp_gt_u32_e32 vcc, s70, v57
	v_add_u32_e32 v57, 2, v56
	v_sub_u32_e32 v58, -2, v56
	v_max_i32_e32 v57, v57, v58
	v_cndmask_b32_e32 v41, v118, v41, vcc
	v_cmp_gt_u32_e32 vcc, s70, v57
	v_add_u32_e32 v57, 3, v56
	v_sub_u32_e32 v56, -3, v56
	v_max_i32_e32 v56, v57, v56
	v_cndmask_b32_e32 v42, v118, v42, vcc
	v_cmp_gt_u32_e32 vcc, s70, v56
	s_nop 1
	v_cndmask_b32_e32 v43, v118, v43, vcc
	s_branch .LBB0_2356

.LBB0_2471:
	s_andn2_saveexec_b64 s[0:1], s[0:1]
	s_cbranch_execz .LBB0_2489
	s_waitcnt vmcnt(16)
	s_mov_b32 s98, 0xaaaaaab
	v_mul_hi_u32 v78, v226, s98
	v_mul_u32_u24_e32 v79, 24, v78
	v_sub_u32_e32 v79, v226, v79
	v_lshlrev_b32_e32 v1, 5, v79
	v_and_b32_e32 v80, 7, v79
	v_mul_u32_u24_e32 v89, 0x480, v78
	v_lshl_add_u32 v89, v80, 4, v89
	v_cmp_gt_u32_e32 vcc, 16, v79
	v_mul_u32_u24_e32 v143, 0x480, v80
	v_lshl_add_u32 v143, v78, 4, v143
	v_mov_b32_e32 v78, 0x2400
	v_cndmask_b32_e32 v78, 0, v78, vcc
	v_add_u32_e32 v89, v89, v78
	v_cmp_gt_u32_e32 vcc, 8, v79
	v_mov_b32_e32 v78, 0x6c00
	v_mov_b32_e32 v80, 0x4800
	s_nop 0
	v_cndmask_b32_e32 v78, v78, v80, vcc
	v_add_u32_e32 v143, v143, v78
	s_mov_b32 s98, 0xbfb8aa3b
	s_mov_b32 s99, s98
	ds_read_b64 v[66:67], v1 offset:46848
	ds_read_b64 v[68:69], v1 offset:47616
	ds_read_b64 v[70:71], v1 offset:48384
	ds_read_b64 v[72:73], v1 offset:49152
	ds_read_b64 v[74:75], v1 offset:49920
	ds_read_b64 v[76:77], v1 offset:50688
	v_lshlrev_b32_e32 v78, 16, v18
	v_and_b32_e32 v79, 0xffff0000, v18
	v_lshlrev_b32_e32 v80, 16, v14
	v_and_b32_e32 v81, 0xffff0000, v14
	v_lshlrev_b32_e32 v82, 16, v22
	v_and_b32_e32 v83, 0xffff0000, v22
	v_lshlrev_b32_e32 v84, 16, v30
	v_and_b32_e32 v85, 0xffff0000, v30
	v_lshlrev_b32_e32 v144, 16, v34
	v_and_b32_e32 v145, 0xffff0000, v34
	v_lshlrev_b32_e32 v146, 16, v38
	v_and_b32_e32 v147, 0xffff0000, v38
	v_lshlrev_b32_e32 v148, 16, v42
	v_and_b32_e32 v149, 0xffff0000, v42
	v_lshlrev_b32_e32 v150, 16, v46
	v_and_b32_e32 v151, 0xffff0000, v46
	v_lshlrev_b32_e32 v152, 16, v50
	v_and_b32_e32 v153, 0xffff0000, v50
	v_lshlrev_b32_e32 v154, 16, v54
	v_and_b32_e32 v155, 0xffff0000, v54
	v_lshlrev_b32_e32 v156, 16, v58
	v_and_b32_e32 v157, 0xffff0000, v58
	v_lshlrev_b32_e32 v158, 16, v62
	v_and_b32_e32 v159, 0xffff0000, v62
	s_waitcnt lgkmcnt(0)
	v_pk_fma_f32 v[106:107], v[66:67], v[78:79], v[76:77]
	v_pk_fma_f32 v[106:107], v[68:69], v[80:81], v[106:107]
	v_pk_fma_f32 v[106:107], v[70:71], v[82:83], v[106:107]
	v_pk_fma_f32 v[106:107], v[72:73], v[84:85], v[106:107]
	v_pk_fma_f32 v[106:107], v[74:75], v[144:145], v[106:107]
	v_pk_mul_f32 v[242:243], v[106:107], s[98:99]
	v_exp_f32_e32 v242, v242
	v_exp_f32_e32 v243, v243
	v_pk_fma_f32 v[244:245], v[66:67], v[80:81], v[76:77]
	v_pk_add_f32 v[242:243], v[242:243], 1.0 op_sel_hi:[1,0]
	v_rcp_f32_e32 v242, v242
	v_rcp_f32_e32 v243, v243
	v_pk_fma_f32 v[244:245], v[68:69], v[82:83], v[244:245]
	v_pk_mul_f32 v[78:79], v[106:107], v[242:243]
	v_pk_fma_f32 v[244:245], v[70:71], v[84:85], v[244:245]
	v_pk_fma_f32 v[244:245], v[72:73], v[144:145], v[244:245]
	v_pk_fma_f32 v[244:245], v[74:75], v[146:147], v[244:245]
	v_pk_mul_f32 v[242:243], v[244:245], s[98:99]
	v_exp_f32_e32 v242, v242
	v_exp_f32_e32 v243, v243
	v_pk_fma_f32 v[106:107], v[66:67], v[82:83], v[76:77]
	v_pk_add_f32 v[242:243], v[242:243], 1.0 op_sel_hi:[1,0]
	v_rcp_f32_e32 v242, v242
	v_rcp_f32_e32 v243, v243
	v_pk_fma_f32 v[106:107], v[68:69], v[84:85], v[106:107]
	v_pk_mul_f32 v[80:81], v[244:245], v[242:243]
	v_pk_fma_f32 v[106:107], v[70:71], v[144:145], v[106:107]
	v_pk_fma_f32 v[106:107], v[72:73], v[146:147], v[106:107]
	v_pk_fma_f32 v[106:107], v[74:75], v[148:149], v[106:107]
	v_pk_mul_f32 v[242:243], v[106:107], s[98:99]
	v_exp_f32_e32 v242, v242
	v_exp_f32_e32 v243, v243
	v_pk_fma_f32 v[244:245], v[66:67], v[84:85], v[76:77]
	v_pk_add_f32 v[242:243], v[242:243], 1.0 op_sel_hi:[1,0]
	v_rcp_f32_e32 v242, v242
	v_rcp_f32_e32 v243, v243
	v_pk_fma_f32 v[244:245], v[68:69], v[144:145], v[244:245]
	v_pk_mul_f32 v[82:83], v[106:107], v[242:243]
	v_pk_fma_f32 v[244:245], v[70:71], v[146:147], v[244:245]
	v_pk_fma_f32 v[244:245], v[72:73], v[148:149], v[244:245]
	v_pk_fma_f32 v[244:245], v[74:75], v[150:151], v[244:245]
	v_pk_mul_f32 v[242:243], v[244:245], s[98:99]
	v_exp_f32_e32 v242, v242
	v_exp_f32_e32 v243, v243
	v_pk_fma_f32 v[106:107], v[66:67], v[144:145], v[76:77]
	v_pk_add_f32 v[242:243], v[242:243], 1.0 op_sel_hi:[1,0]
	v_rcp_f32_e32 v242, v242
	v_rcp_f32_e32 v243, v243
	v_pk_fma_f32 v[106:107], v[68:69], v[146:147], v[106:107]
	v_pk_mul_f32 v[84:85], v[244:245], v[242:243]
	v_pk_fma_f32 v[106:107], v[70:71], v[148:149], v[106:107]
	v_pk_fma_f32 v[106:107], v[72:73], v[150:151], v[106:107]
	v_pk_fma_f32 v[106:107], v[74:75], v[152:153], v[106:107]
	v_pk_mul_f32 v[242:243], v[106:107], s[98:99]
	v_exp_f32_e32 v242, v242
	v_exp_f32_e32 v243, v243
	v_pk_fma_f32 v[244:245], v[66:67], v[146:147], v[76:77]
	v_pk_add_f32 v[242:243], v[242:243], 1.0 op_sel_hi:[1,0]
	v_rcp_f32_e32 v242, v242
	v_rcp_f32_e32 v243, v243
	v_pk_fma_f32 v[244:245], v[68:69], v[148:149], v[244:245]
	v_pk_mul_f32 v[144:145], v[106:107], v[242:243]
	v_pk_fma_f32 v[244:245], v[70:71], v[150:151], v[244:245]
	v_pk_fma_f32 v[244:245], v[72:73], v[152:153], v[244:245]
	v_pk_fma_f32 v[244:245], v[74:75], v[154:155], v[244:245]
	v_pk_mul_f32 v[242:243], v[244:245], s[98:99]
	v_exp_f32_e32 v242, v242
	v_exp_f32_e32 v243, v243
	v_pk_fma_f32 v[106:107], v[66:67], v[148:149], v[76:77]
	v_pk_add_f32 v[242:243], v[242:243], 1.0 op_sel_hi:[1,0]
	v_rcp_f32_e32 v242, v242
	v_rcp_f32_e32 v243, v243
	v_pk_fma_f32 v[106:107], v[68:69], v[150:151], v[106:107]
	v_pk_mul_f32 v[146:147], v[244:245], v[242:243]
	v_pk_fma_f32 v[106:107], v[70:71], v[152:153], v[106:107]
	v_pk_fma_f32 v[106:107], v[72:73], v[154:155], v[106:107]
	v_pk_fma_f32 v[106:107], v[74:75], v[156:157], v[106:107]
	v_pk_mul_f32 v[242:243], v[106:107], s[98:99]
	v_exp_f32_e32 v242, v242
	v_exp_f32_e32 v243, v243
	v_pk_fma_f32 v[244:245], v[66:67], v[150:151], v[76:77]
	v_pk_add_f32 v[242:243], v[242:243], 1.0 op_sel_hi:[1,0]
	v_rcp_f32_e32 v242, v242
	v_rcp_f32_e32 v243, v243
	v_pk_fma_f32 v[244:245], v[68:69], v[152:153], v[244:245]
	v_pk_mul_f32 v[148:149], v[106:107], v[242:243]
	v_pk_fma_f32 v[244:245], v[70:71], v[154:155], v[244:245]
	v_pk_fma_f32 v[244:245], v[72:73], v[156:157], v[244:245]
	v_pk_fma_f32 v[244:245], v[74:75], v[158:159], v[244:245]
	v_pk_mul_f32 v[242:243], v[244:245], s[98:99]
	v_exp_f32_e32 v242, v242
	v_exp_f32_e32 v243, v243
	s_nop 0
	v_pk_add_f32 v[242:243], v[242:243], 1.0 op_sel_hi:[1,0]
	v_rcp_f32_e32 v242, v242
	v_rcp_f32_e32 v243, v243
	s_nop 0
	v_pk_mul_f32 v[150:151], v[244:245], v[242:243]
	s_and_saveexec_b64 s[58:59], s[8:9]
	s_cbranch_execz .LssdA1_r0
	v_cvt_pk_bf16_f32 v70, v78, v79
	v_cvt_pk_bf16_f32 v71, v80, v81
	ds_write2_b32 v89, v70, v71 offset0:0 offset1:36
	v_cvt_pk_bf16_f32 v70, v82, v83
	v_cvt_pk_bf16_f32 v71, v84, v85
	ds_write2_b32 v89, v70, v71 offset0:72 offset1:108
	v_cvt_pk_bf16_f32 v70, v144, v145
	v_cvt_pk_bf16_f32 v71, v146, v147
	ds_write2_b32 v89, v70, v71 offset0:144 offset1:180
	v_cvt_pk_bf16_f32 v70, v148, v149
	v_cvt_pk_bf16_f32 v71, v150, v151
	ds_write2_b32 v89, v70, v71 offset0:216 offset1:252

.LssdA1_t0:
	s_or_b64 exec, exec, s[58:59]
	ds_read_b64 v[66:67], v1 offset:46856
	ds_read_b64 v[68:69], v1 offset:47624
	ds_read_b64 v[70:71], v1 offset:48392
	ds_read_b64 v[72:73], v1 offset:49160
	ds_read_b64 v[74:75], v1 offset:49928
	ds_read_b64 v[76:77], v1 offset:50696
	v_lshlrev_b32_e32 v78, 16, v19
	v_and_b32_e32 v79, 0xffff0000, v19
	v_lshlrev_b32_e32 v80, 16, v15
	v_and_b32_e32 v81, 0xffff0000, v15
	v_lshlrev_b32_e32 v82, 16, v23
	v_and_b32_e32 v83, 0xffff0000, v23
	v_lshlrev_b32_e32 v84, 16, v31
	v_and_b32_e32 v85, 0xffff0000, v31
	v_lshlrev_b32_e32 v144, 16, v35
	v_and_b32_e32 v145, 0xffff0000, v35
	v_lshlrev_b32_e32 v146, 16, v39
	v_and_b32_e32 v147, 0xffff0000, v39
	v_lshlrev_b32_e32 v148, 16, v43
	v_and_b32_e32 v149, 0xffff0000, v43
	v_lshlrev_b32_e32 v150, 16, v47
	v_and_b32_e32 v151, 0xffff0000, v47
	v_lshlrev_b32_e32 v152, 16, v51
	v_and_b32_e32 v153, 0xffff0000, v51
	v_lshlrev_b32_e32 v154, 16, v55
	v_and_b32_e32 v155, 0xffff0000, v55
	v_lshlrev_b32_e32 v156, 16, v59
	v_and_b32_e32 v157, 0xffff0000, v59
	v_lshlrev_b32_e32 v158, 16, v63
	v_and_b32_e32 v159, 0xffff0000, v63
	s_waitcnt lgkmcnt(0)
	v_pk_fma_f32 v[106:107], v[66:67], v[78:79], v[76:77]
	v_pk_fma_f32 v[106:107], v[68:69], v[80:81], v[106:107]
	v_pk_fma_f32 v[106:107], v[70:71], v[82:83], v[106:107]
	v_pk_fma_f32 v[106:107], v[72:73], v[84:85], v[106:107]
	v_pk_fma_f32 v[106:107], v[74:75], v[144:145], v[106:107]
	v_pk_mul_f32 v[242:243], v[106:107], s[98:99]
	v_exp_f32_e32 v242, v242
	v_exp_f32_e32 v243, v243
	v_pk_fma_f32 v[244:245], v[66:67], v[80:81], v[76:77]
	v_pk_add_f32 v[242:243], v[242:243], 1.0 op_sel_hi:[1,0]
	v_rcp_f32_e32 v242, v242
	v_rcp_f32_e32 v243, v243
	v_pk_fma_f32 v[244:245], v[68:69], v[82:83], v[244:245]
	v_pk_mul_f32 v[78:79], v[106:107], v[242:243]
	v_pk_fma_f32 v[244:245], v[70:71], v[84:85], v[244:245]
	v_pk_fma_f32 v[244:245], v[72:73], v[144:145], v[244:245]
	v_pk_fma_f32 v[244:245], v[74:75], v[146:147], v[244:245]
	v_pk_mul_f32 v[242:243], v[244:245], s[98:99]
	v_exp_f32_e32 v242, v242
	v_exp_f32_e32 v243, v243
	v_pk_fma_f32 v[106:107], v[66:67], v[82:83], v[76:77]
	v_pk_add_f32 v[242:243], v[242:243], 1.0 op_sel_hi:[1,0]
	v_rcp_f32_e32 v242, v242
	v_rcp_f32_e32 v243, v243
	v_pk_fma_f32 v[106:107], v[68:69], v[84:85], v[106:107]
	v_pk_mul_f32 v[80:81], v[244:245], v[242:243]
	v_pk_fma_f32 v[106:107], v[70:71], v[144:145], v[106:107]
	v_pk_fma_f32 v[106:107], v[72:73], v[146:147], v[106:107]
	v_pk_fma_f32 v[106:107], v[74:75], v[148:149], v[106:107]
	v_pk_mul_f32 v[242:243], v[106:107], s[98:99]
	v_exp_f32_e32 v242, v242
	v_exp_f32_e32 v243, v243
	v_pk_fma_f32 v[244:245], v[66:67], v[84:85], v[76:77]
	v_pk_add_f32 v[242:243], v[242:243], 1.0 op_sel_hi:[1,0]
	v_rcp_f32_e32 v242, v242
	v_rcp_f32_e32 v243, v243
	v_pk_fma_f32 v[244:245], v[68:69], v[144:145], v[244:245]
	v_pk_mul_f32 v[82:83], v[106:107], v[242:243]
	v_pk_fma_f32 v[244:245], v[70:71], v[146:147], v[244:245]
	v_pk_fma_f32 v[244:245], v[72:73], v[148:149], v[244:245]
	v_pk_fma_f32 v[244:245], v[74:75], v[150:151], v[244:245]
	v_pk_mul_f32 v[242:243], v[244:245], s[98:99]
	v_exp_f32_e32 v242, v242
	v_exp_f32_e32 v243, v243
	v_pk_fma_f32 v[106:107], v[66:67], v[144:145], v[76:77]
	v_pk_add_f32 v[242:243], v[242:243], 1.0 op_sel_hi:[1,0]
	v_rcp_f32_e32 v242, v242
	v_rcp_f32_e32 v243, v243
	v_pk_fma_f32 v[106:107], v[68:69], v[146:147], v[106:107]
	v_pk_mul_f32 v[84:85], v[244:245], v[242:243]
	v_pk_fma_f32 v[106:107], v[70:71], v[148:149], v[106:107]
	v_pk_fma_f32 v[106:107], v[72:73], v[150:151], v[106:107]
	v_pk_fma_f32 v[106:107], v[74:75], v[152:153], v[106:107]
	v_pk_mul_f32 v[242:243], v[106:107], s[98:99]
	v_exp_f32_e32 v242, v242
	v_exp_f32_e32 v243, v243
	v_pk_fma_f32 v[244:245], v[66:67], v[146:147], v[76:77]
	v_pk_add_f32 v[242:243], v[242:243], 1.0 op_sel_hi:[1,0]
	v_rcp_f32_e32 v242, v242
	v_rcp_f32_e32 v243, v243
	v_pk_fma_f32 v[244:245], v[68:69], v[148:149], v[244:245]
	v_pk_mul_f32 v[144:145], v[106:107], v[242:243]
	v_pk_fma_f32 v[244:245], v[70:71], v[150:151], v[244:245]
	v_pk_fma_f32 v[244:245], v[72:73], v[152:153], v[244:245]
	v_pk_fma_f32 v[244:245], v[74:75], v[154:155], v[244:245]
	v_pk_mul_f32 v[242:243], v[244:245], s[98:99]
	v_exp_f32_e32 v242, v242
	v_exp_f32_e32 v243, v243
	v_pk_fma_f32 v[106:107], v[66:67], v[148:149], v[76:77]
	v_pk_add_f32 v[242:243], v[242:243], 1.0 op_sel_hi:[1,0]
	v_rcp_f32_e32 v242, v242
	v_rcp_f32_e32 v243, v243
	v_pk_fma_f32 v[106:107], v[68:69], v[150:151], v[106:107]
	v_pk_mul_f32 v[146:147], v[244:245], v[242:243]
	v_pk_fma_f32 v[106:107], v[70:71], v[152:153], v[106:107]
	v_pk_fma_f32 v[106:107], v[72:73], v[154:155], v[106:107]
	v_pk_fma_f32 v[106:107], v[74:75], v[156:157], v[106:107]
	v_pk_mul_f32 v[242:243], v[106:107], s[98:99]
	v_exp_f32_e32 v242, v242
	v_exp_f32_e32 v243, v243
	v_pk_fma_f32 v[244:245], v[66:67], v[150:151], v[76:77]
	v_pk_add_f32 v[242:243], v[242:243], 1.0 op_sel_hi:[1,0]
	v_rcp_f32_e32 v242, v242
	v_rcp_f32_e32 v243, v243
	v_pk_fma_f32 v[244:245], v[68:69], v[152:153], v[244:245]
	v_pk_mul_f32 v[148:149], v[106:107], v[242:243]
	v_pk_fma_f32 v[244:245], v[70:71], v[154:155], v[244:245]
	v_pk_fma_f32 v[244:245], v[72:73], v[156:157], v[244:245]
	v_pk_fma_f32 v[244:245], v[74:75], v[158:159], v[244:245]
	v_pk_mul_f32 v[242:243], v[244:245], s[98:99]
	v_exp_f32_e32 v242, v242
	v_exp_f32_e32 v243, v243
	s_nop 0
	v_pk_add_f32 v[242:243], v[242:243], 1.0 op_sel_hi:[1,0]
	v_rcp_f32_e32 v242, v242
	v_rcp_f32_e32 v243, v243
	s_nop 0
	v_pk_mul_f32 v[150:151], v[244:245], v[242:243]
	s_and_saveexec_b64 s[58:59], s[8:9]
	s_cbranch_execz .LssdA1_r1
	v_cvt_pk_bf16_f32 v70, v78, v79
	v_cvt_pk_bf16_f32 v71, v80, v81
	ds_write2_b32 v89, v70, v71 offset0:1 offset1:37
	v_cvt_pk_bf16_f32 v70, v82, v83
	v_cvt_pk_bf16_f32 v71, v84, v85
	ds_write2_b32 v89, v70, v71 offset0:73 offset1:109
	v_cvt_pk_bf16_f32 v70, v144, v145
	v_cvt_pk_bf16_f32 v71, v146, v147
	ds_write2_b32 v89, v70, v71 offset0:145 offset1:181
	v_cvt_pk_bf16_f32 v70, v148, v149
	v_cvt_pk_bf16_f32 v71, v150, v151
	ds_write2_b32 v89, v70, v71 offset0:217 offset1:253

.LssdA1_t1:
	s_or_b64 exec, exec, s[58:59]
	ds_read_b64 v[66:67], v1 offset:46864
	ds_read_b64 v[68:69], v1 offset:47632
	ds_read_b64 v[70:71], v1 offset:48400
	ds_read_b64 v[72:73], v1 offset:49168
	ds_read_b64 v[74:75], v1 offset:49936
	ds_read_b64 v[76:77], v1 offset:50704
	v_lshlrev_b32_e32 v78, 16, v20
	v_and_b32_e32 v79, 0xffff0000, v20
	v_lshlrev_b32_e32 v80, 16, v16
	v_and_b32_e32 v81, 0xffff0000, v16
	v_lshlrev_b32_e32 v82, 16, v24
	v_and_b32_e32 v83, 0xffff0000, v24
	v_lshlrev_b32_e32 v84, 16, v32
	v_and_b32_e32 v85, 0xffff0000, v32
	v_lshlrev_b32_e32 v144, 16, v36
	v_and_b32_e32 v145, 0xffff0000, v36
	v_lshlrev_b32_e32 v146, 16, v40
	v_and_b32_e32 v147, 0xffff0000, v40
	v_lshlrev_b32_e32 v148, 16, v44
	v_and_b32_e32 v149, 0xffff0000, v44
	v_lshlrev_b32_e32 v150, 16, v48
	v_and_b32_e32 v151, 0xffff0000, v48
	v_lshlrev_b32_e32 v152, 16, v52
	v_and_b32_e32 v153, 0xffff0000, v52
	v_lshlrev_b32_e32 v154, 16, v56
	v_and_b32_e32 v155, 0xffff0000, v56
	v_lshlrev_b32_e32 v156, 16, v60
	v_and_b32_e32 v157, 0xffff0000, v60
	v_lshlrev_b32_e32 v158, 16, v64
	v_and_b32_e32 v159, 0xffff0000, v64
	s_waitcnt lgkmcnt(0)
	v_pk_fma_f32 v[106:107], v[66:67], v[78:79], v[76:77]
	v_pk_fma_f32 v[106:107], v[68:69], v[80:81], v[106:107]
	v_pk_fma_f32 v[106:107], v[70:71], v[82:83], v[106:107]
	v_pk_fma_f32 v[106:107], v[72:73], v[84:85], v[106:107]
	v_pk_fma_f32 v[106:107], v[74:75], v[144:145], v[106:107]
	v_pk_mul_f32 v[242:243], v[106:107], s[98:99]
	v_exp_f32_e32 v242, v242
	v_exp_f32_e32 v243, v243
	v_pk_fma_f32 v[244:245], v[66:67], v[80:81], v[76:77]
	v_pk_add_f32 v[242:243], v[242:243], 1.0 op_sel_hi:[1,0]
	v_rcp_f32_e32 v242, v242
	v_rcp_f32_e32 v243, v243
	v_pk_fma_f32 v[244:245], v[68:69], v[82:83], v[244:245]
	v_pk_mul_f32 v[78:79], v[106:107], v[242:243]
	v_pk_fma_f32 v[244:245], v[70:71], v[84:85], v[244:245]
	v_pk_fma_f32 v[244:245], v[72:73], v[144:145], v[244:245]
	v_pk_fma_f32 v[244:245], v[74:75], v[146:147], v[244:245]
	v_pk_mul_f32 v[242:243], v[244:245], s[98:99]
	v_exp_f32_e32 v242, v242
	v_exp_f32_e32 v243, v243
	v_pk_fma_f32 v[106:107], v[66:67], v[82:83], v[76:77]
	v_pk_add_f32 v[242:243], v[242:243], 1.0 op_sel_hi:[1,0]
	v_rcp_f32_e32 v242, v242
	v_rcp_f32_e32 v243, v243
	v_pk_fma_f32 v[106:107], v[68:69], v[84:85], v[106:107]
	v_pk_mul_f32 v[80:81], v[244:245], v[242:243]
	v_pk_fma_f32 v[106:107], v[70:71], v[144:145], v[106:107]
	v_pk_fma_f32 v[106:107], v[72:73], v[146:147], v[106:107]
	v_pk_fma_f32 v[106:107], v[74:75], v[148:149], v[106:107]
	v_pk_mul_f32 v[242:243], v[106:107], s[98:99]
	v_exp_f32_e32 v242, v242
	v_exp_f32_e32 v243, v243
	v_pk_fma_f32 v[244:245], v[66:67], v[84:85], v[76:77]
	v_pk_add_f32 v[242:243], v[242:243], 1.0 op_sel_hi:[1,0]
	v_rcp_f32_e32 v242, v242
	v_rcp_f32_e32 v243, v243
	v_pk_fma_f32 v[244:245], v[68:69], v[144:145], v[244:245]
	v_pk_mul_f32 v[82:83], v[106:107], v[242:243]
	v_pk_fma_f32 v[244:245], v[70:71], v[146:147], v[244:245]
	v_pk_fma_f32 v[244:245], v[72:73], v[148:149], v[244:245]
	v_pk_fma_f32 v[244:245], v[74:75], v[150:151], v[244:245]
	v_pk_mul_f32 v[242:243], v[244:245], s[98:99]
	v_exp_f32_e32 v242, v242
	v_exp_f32_e32 v243, v243
	v_pk_fma_f32 v[106:107], v[66:67], v[144:145], v[76:77]
	v_pk_add_f32 v[242:243], v[242:243], 1.0 op_sel_hi:[1,0]
	v_rcp_f32_e32 v242, v242
	v_rcp_f32_e32 v243, v243
	v_pk_fma_f32 v[106:107], v[68:69], v[146:147], v[106:107]
	v_pk_mul_f32 v[84:85], v[244:245], v[242:243]
	v_pk_fma_f32 v[106:107], v[70:71], v[148:149], v[106:107]
	v_pk_fma_f32 v[106:107], v[72:73], v[150:151], v[106:107]
	v_pk_fma_f32 v[106:107], v[74:75], v[152:153], v[106:107]
	v_pk_mul_f32 v[242:243], v[106:107], s[98:99]
	v_exp_f32_e32 v242, v242
	v_exp_f32_e32 v243, v243
	v_pk_fma_f32 v[244:245], v[66:67], v[146:147], v[76:77]
	v_pk_add_f32 v[242:243], v[242:243], 1.0 op_sel_hi:[1,0]
	v_rcp_f32_e32 v242, v242
	v_rcp_f32_e32 v243, v243
	v_pk_fma_f32 v[244:245], v[68:69], v[148:149], v[244:245]
	v_pk_mul_f32 v[144:145], v[106:107], v[242:243]
	v_pk_fma_f32 v[244:245], v[70:71], v[150:151], v[244:245]
	v_pk_fma_f32 v[244:245], v[72:73], v[152:153], v[244:245]
	v_pk_fma_f32 v[244:245], v[74:75], v[154:155], v[244:245]
	v_pk_mul_f32 v[242:243], v[244:245], s[98:99]
	v_exp_f32_e32 v242, v242
	v_exp_f32_e32 v243, v243
	v_pk_fma_f32 v[106:107], v[66:67], v[148:149], v[76:77]
	v_pk_add_f32 v[242:243], v[242:243], 1.0 op_sel_hi:[1,0]
	v_rcp_f32_e32 v242, v242
	v_rcp_f32_e32 v243, v243
	v_pk_fma_f32 v[106:107], v[68:69], v[150:151], v[106:107]
	v_pk_mul_f32 v[146:147], v[244:245], v[242:243]
	v_pk_fma_f32 v[106:107], v[70:71], v[152:153], v[106:107]
	v_pk_fma_f32 v[106:107], v[72:73], v[154:155], v[106:107]
	v_pk_fma_f32 v[106:107], v[74:75], v[156:157], v[106:107]
	v_pk_mul_f32 v[242:243], v[106:107], s[98:99]
	v_exp_f32_e32 v242, v242
	v_exp_f32_e32 v243, v243
	v_pk_fma_f32 v[244:245], v[66:67], v[150:151], v[76:77]
	v_pk_add_f32 v[242:243], v[242:243], 1.0 op_sel_hi:[1,0]
	v_rcp_f32_e32 v242, v242
	v_rcp_f32_e32 v243, v243
	v_pk_fma_f32 v[244:245], v[68:69], v[152:153], v[244:245]
	v_pk_mul_f32 v[148:149], v[106:107], v[242:243]
	v_pk_fma_f32 v[244:245], v[70:71], v[154:155], v[244:245]
	v_pk_fma_f32 v[244:245], v[72:73], v[156:157], v[244:245]
	v_pk_fma_f32 v[244:245], v[74:75], v[158:159], v[244:245]
	v_pk_mul_f32 v[242:243], v[244:245], s[98:99]
	v_exp_f32_e32 v242, v242
	v_exp_f32_e32 v243, v243
	s_nop 0
	v_pk_add_f32 v[242:243], v[242:243], 1.0 op_sel_hi:[1,0]
	v_rcp_f32_e32 v242, v242
	v_rcp_f32_e32 v243, v243
	s_nop 0
	v_pk_mul_f32 v[150:151], v[244:245], v[242:243]
	s_and_saveexec_b64 s[58:59], s[8:9]
	s_cbranch_execz .LssdA1_r2
	v_cvt_pk_bf16_f32 v70, v78, v79
	v_cvt_pk_bf16_f32 v71, v80, v81
	ds_write2_b32 v89, v70, v71 offset0:2 offset1:38
	v_cvt_pk_bf16_f32 v70, v82, v83
	v_cvt_pk_bf16_f32 v71, v84, v85
	ds_write2_b32 v89, v70, v71 offset0:74 offset1:110
	v_cvt_pk_bf16_f32 v70, v144, v145
	v_cvt_pk_bf16_f32 v71, v146, v147
	ds_write2_b32 v89, v70, v71 offset0:146 offset1:182
	v_cvt_pk_bf16_f32 v70, v148, v149
	v_cvt_pk_bf16_f32 v71, v150, v151
	ds_write2_b32 v89, v70, v71 offset0:218 offset1:254

.LssdA1_t2:
	s_or_b64 exec, exec, s[58:59]
	ds_read_b64 v[66:67], v1 offset:46872
	ds_read_b64 v[68:69], v1 offset:47640
	ds_read_b64 v[70:71], v1 offset:48408
	ds_read_b64 v[72:73], v1 offset:49176
	ds_read_b64 v[74:75], v1 offset:49944
	ds_read_b64 v[76:77], v1 offset:50712
	v_lshlrev_b32_e32 v78, 16, v21
	v_and_b32_e32 v79, 0xffff0000, v21
	v_lshlrev_b32_e32 v80, 16, v17
	v_and_b32_e32 v81, 0xffff0000, v17
	v_lshlrev_b32_e32 v82, 16, v25
	v_and_b32_e32 v83, 0xffff0000, v25
	v_lshlrev_b32_e32 v84, 16, v33
	v_and_b32_e32 v85, 0xffff0000, v33
	v_lshlrev_b32_e32 v144, 16, v37
	v_and_b32_e32 v145, 0xffff0000, v37
	v_lshlrev_b32_e32 v146, 16, v41
	v_and_b32_e32 v147, 0xffff0000, v41
	v_lshlrev_b32_e32 v148, 16, v45
	v_and_b32_e32 v149, 0xffff0000, v45
	v_lshlrev_b32_e32 v150, 16, v49
	v_and_b32_e32 v151, 0xffff0000, v49
	v_lshlrev_b32_e32 v152, 16, v53
	v_and_b32_e32 v153, 0xffff0000, v53
	v_lshlrev_b32_e32 v154, 16, v57
	v_and_b32_e32 v155, 0xffff0000, v57
	v_lshlrev_b32_e32 v156, 16, v61
	v_and_b32_e32 v157, 0xffff0000, v61
	v_lshlrev_b32_e32 v158, 16, v65
	v_and_b32_e32 v159, 0xffff0000, v65
	s_waitcnt lgkmcnt(0)
	v_pk_fma_f32 v[106:107], v[66:67], v[78:79], v[76:77]
	v_pk_fma_f32 v[106:107], v[68:69], v[80:81], v[106:107]
	v_pk_fma_f32 v[106:107], v[70:71], v[82:83], v[106:107]
	v_pk_fma_f32 v[106:107], v[72:73], v[84:85], v[106:107]
	v_pk_fma_f32 v[106:107], v[74:75], v[144:145], v[106:107]
	v_pk_mul_f32 v[242:243], v[106:107], s[98:99]
	v_exp_f32_e32 v242, v242
	v_exp_f32_e32 v243, v243
	v_pk_fma_f32 v[244:245], v[66:67], v[80:81], v[76:77]
	v_pk_add_f32 v[242:243], v[242:243], 1.0 op_sel_hi:[1,0]
	v_rcp_f32_e32 v242, v242
	v_rcp_f32_e32 v243, v243
	v_pk_fma_f32 v[244:245], v[68:69], v[82:83], v[244:245]
	v_pk_mul_f32 v[78:79], v[106:107], v[242:243]
	v_pk_fma_f32 v[244:245], v[70:71], v[84:85], v[244:245]
	v_pk_fma_f32 v[244:245], v[72:73], v[144:145], v[244:245]
	v_pk_fma_f32 v[244:245], v[74:75], v[146:147], v[244:245]
	v_pk_mul_f32 v[242:243], v[244:245], s[98:99]
	v_exp_f32_e32 v242, v242
	v_exp_f32_e32 v243, v243
	v_pk_fma_f32 v[106:107], v[66:67], v[82:83], v[76:77]
	v_pk_add_f32 v[242:243], v[242:243], 1.0 op_sel_hi:[1,0]
	v_rcp_f32_e32 v242, v242
	v_rcp_f32_e32 v243, v243
	v_pk_fma_f32 v[106:107], v[68:69], v[84:85], v[106:107]
	v_pk_mul_f32 v[80:81], v[244:245], v[242:243]
	v_pk_fma_f32 v[106:107], v[70:71], v[144:145], v[106:107]
	v_pk_fma_f32 v[106:107], v[72:73], v[146:147], v[106:107]
	v_pk_fma_f32 v[106:107], v[74:75], v[148:149], v[106:107]
	v_pk_mul_f32 v[242:243], v[106:107], s[98:99]
	v_exp_f32_e32 v242, v242
	v_exp_f32_e32 v243, v243
	v_pk_fma_f32 v[244:245], v[66:67], v[84:85], v[76:77]
	v_pk_add_f32 v[242:243], v[242:243], 1.0 op_sel_hi:[1,0]
	v_rcp_f32_e32 v242, v242
	v_rcp_f32_e32 v243, v243
	v_pk_fma_f32 v[244:245], v[68:69], v[144:145], v[244:245]
	v_pk_mul_f32 v[82:83], v[106:107], v[242:243]
	v_pk_fma_f32 v[244:245], v[70:71], v[146:147], v[244:245]
	v_pk_fma_f32 v[244:245], v[72:73], v[148:149], v[244:245]
	v_pk_fma_f32 v[244:245], v[74:75], v[150:151], v[244:245]
	v_pk_mul_f32 v[242:243], v[244:245], s[98:99]
	v_exp_f32_e32 v242, v242
	v_exp_f32_e32 v243, v243
	v_pk_fma_f32 v[106:107], v[66:67], v[144:145], v[76:77]
	v_pk_add_f32 v[242:243], v[242:243], 1.0 op_sel_hi:[1,0]
	v_rcp_f32_e32 v242, v242
	v_rcp_f32_e32 v243, v243
	v_pk_fma_f32 v[106:107], v[68:69], v[146:147], v[106:107]
	v_pk_mul_f32 v[84:85], v[244:245], v[242:243]
	v_pk_fma_f32 v[106:107], v[70:71], v[148:149], v[106:107]
	v_pk_fma_f32 v[106:107], v[72:73], v[150:151], v[106:107]
	v_pk_fma_f32 v[106:107], v[74:75], v[152:153], v[106:107]
	v_pk_mul_f32 v[242:243], v[106:107], s[98:99]
	v_exp_f32_e32 v242, v242
	v_exp_f32_e32 v243, v243
	v_pk_fma_f32 v[244:245], v[66:67], v[146:147], v[76:77]
	v_pk_add_f32 v[242:243], v[242:243], 1.0 op_sel_hi:[1,0]
	v_rcp_f32_e32 v242, v242
	v_rcp_f32_e32 v243, v243
	v_pk_fma_f32 v[244:245], v[68:69], v[148:149], v[244:245]
	v_pk_mul_f32 v[144:145], v[106:107], v[242:243]
	v_pk_fma_f32 v[244:245], v[70:71], v[150:151], v[244:245]
	v_pk_fma_f32 v[244:245], v[72:73], v[152:153], v[244:245]
	v_pk_fma_f32 v[244:245], v[74:75], v[154:155], v[244:245]
	v_pk_mul_f32 v[242:243], v[244:245], s[98:99]
	v_exp_f32_e32 v242, v242
	v_exp_f32_e32 v243, v243
	v_pk_fma_f32 v[106:107], v[66:67], v[148:149], v[76:77]
	v_pk_add_f32 v[242:243], v[242:243], 1.0 op_sel_hi:[1,0]
	v_rcp_f32_e32 v242, v242
	v_rcp_f32_e32 v243, v243
	v_pk_fma_f32 v[106:107], v[68:69], v[150:151], v[106:107]
	v_pk_mul_f32 v[146:147], v[244:245], v[242:243]
	v_pk_fma_f32 v[106:107], v[70:71], v[152:153], v[106:107]
	v_pk_fma_f32 v[106:107], v[72:73], v[154:155], v[106:107]
	v_pk_fma_f32 v[106:107], v[74:75], v[156:157], v[106:107]
	v_pk_mul_f32 v[242:243], v[106:107], s[98:99]
	v_exp_f32_e32 v242, v242
	v_exp_f32_e32 v243, v243
	v_pk_fma_f32 v[244:245], v[66:67], v[150:151], v[76:77]
	v_pk_add_f32 v[242:243], v[242:243], 1.0 op_sel_hi:[1,0]
	v_rcp_f32_e32 v242, v242
	v_rcp_f32_e32 v243, v243
	v_pk_fma_f32 v[244:245], v[68:69], v[152:153], v[244:245]
	v_pk_mul_f32 v[148:149], v[106:107], v[242:243]
	v_pk_fma_f32 v[244:245], v[70:71], v[154:155], v[244:245]
	v_pk_fma_f32 v[244:245], v[72:73], v[156:157], v[244:245]
	v_pk_fma_f32 v[244:245], v[74:75], v[158:159], v[244:245]
	v_pk_mul_f32 v[242:243], v[244:245], s[98:99]
	v_exp_f32_e32 v242, v242
	v_exp_f32_e32 v243, v243
	s_nop 0
	v_pk_add_f32 v[242:243], v[242:243], 1.0 op_sel_hi:[1,0]
	v_rcp_f32_e32 v242, v242
	v_rcp_f32_e32 v243, v243
	s_nop 0
	v_pk_mul_f32 v[150:151], v[244:245], v[242:243]
	s_and_saveexec_b64 s[58:59], s[8:9]
	s_cbranch_execz .LssdA1_r3
	v_cvt_pk_bf16_f32 v70, v78, v79
	v_cvt_pk_bf16_f32 v71, v80, v81
	ds_write2_b32 v89, v70, v71 offset0:3 offset1:39
	v_cvt_pk_bf16_f32 v70, v82, v83
	v_cvt_pk_bf16_f32 v71, v84, v85
	ds_write2_b32 v89, v70, v71 offset0:75 offset1:111
	v_cvt_pk_bf16_f32 v70, v144, v145
	v_cvt_pk_bf16_f32 v71, v146, v147
	ds_write2_b32 v89, v70, v71 offset0:147 offset1:183
	v_cvt_pk_bf16_f32 v70, v148, v149
	v_cvt_pk_bf16_f32 v71, v150, v151
	ds_write2_b32 v89, v70, v71 offset0:219 offset1:255
